# fuse2: H stored as 16-byte pieces via v_permlane16_swap (64 B per row and wave), write-through
# speedup vs baseline: 1.1832x; 1.0014x over previous
.Lf2_nosync:
	s_barrier
	s_and_b32 s9, s72, 7
	s_lshl_b32 s9, s9, 3
	s_bfe_u32 s11, s72, 0x30003
	s_or_b32 s9, s9, s11
	s_lshr_b32 s10, s72, 6
	v_and_b32_e32 v234, 15, v233
	v_lshrrev_b32_e32 v235, 4, v233
	s_and_b32 s11, s8, 3
	s_lshr_b32 s12, s8, 2
	s_lshl_b32 s12, s12, 6
	v_add_u32_e32 v236, s12, v234
	s_lshl_b32 s12, s11, 5
	v_lshl_add_u32 v237, v235, 2, s12
	v_lshl_add_u32 v230, v236, 4, v235
	s_lshl_b32 s12, s11, 2
	v_add_u32_e32 v230, s12, v230
	v_lshlrev_b32_e32 v230, 2, v230
	s_lshl_b32 s12, s10, 8
	v_add_u32_e32 v229, s12, v237
	v_lshlrev_b32_e32 v229, 2, v229
	s_lshl_b32 s12, s9, 8
	v_add_u32_e32 v228, s12, v236
	v_lshl_add_u32 v228, v228, 12, v229
	v_lshrrev_b32_e32 v231, 1, v228
	s_sub_u32 s0, s0, 0x2000000
	s_subb_u32 s1, s1, 0
	s_cmp_lt_u32 s9, 32
	s_cselect_b32 s46, s46, s0
	s_cselect_b32 s47, s47, s1
	s_sub_u32 s11, s9, 32
	s_lshr_b32 s11, s11, 4
	s_add_u32 s11, s11, 1
	s_cmp_lt_u32 s9, 32
	s_cselect_b32 s11, 0, s11
	s_mul_i32 s11, s11, 0x6000
	s_add_u32 s11, s40, s11
	s_addc_u32 s12, s41, 0
	s_add_u32 s48, s11, 0x2000
	s_addc_u32 s49, s12, 0
	s_add_u32 s60, s11, 0x3000
	s_addc_u32 s61, s12, 0
	s_add_u32 s58, s11, 0x4000
	s_addc_u32 s59, s12, 0
	s_add_u32 s52, s40, 0xf984000
	s_addc_u32 s53, s41, 0
	s_add_u32 s54, s40, 0x1380000
	s_addc_u32 s55, s41, 0
	global_load_dwordx4 v[144:147], v229, s[48:49]
	global_load_dwordx4 v[148:151], v229, s[48:49] offset:64
	global_load_dwordx4 v[152:155], v229, s[48:49] offset:512
	global_load_dwordx4 v[156:159], v229, s[48:49] offset:576
	v_and_b32_e32 v238, 1, v235
	v_lshlrev_b32_e32 v238, 5, v238
	v_lshrrev_b32_e32 v239, 1, v235
	v_lshl_add_u32 v238, v239, 4, v238
	v_lshlrev_b32_e32 v239, 3, v235
	v_sub_u32_e32 v238, v238, v239
	v_add_u32_e32 v231, v231, v238
	global_load_dwordx4 v[160:163], v229, s[56:57]
	global_load_dwordx4 v[164:167], v229, s[56:57] offset:64
	global_load_dwordx4 v[168:171], v229, s[56:57] offset:512
	global_load_dwordx4 v[172:175], v229, s[56:57] offset:576
	global_load_dwordx4 v[80:83], v229, s[58:59]
	global_load_dwordx4 v[84:87], v229, s[58:59] offset:64
	global_load_dwordx4 v[88:91], v229, s[58:59] offset:512
	global_load_dwordx4 v[92:95], v229, s[58:59] offset:576
	s_add_u32 s50, s46, 0x0
	s_addc_u32 s51, s47, 0
	global_load_dwordx4 v[180:183], v228, s[50:51]
	global_load_dwordx4 v[184:187], v228, s[50:51] offset:64
	global_load_dwordx4 v[188:191], v228, s[50:51] offset:512
	global_load_dwordx4 v[192:195], v228, s[50:51] offset:576
	s_add_u32 s50, s46, 0x10000
	s_addc_u32 s51, s47, 0
	global_load_dwordx4 v[196:199], v228, s[50:51]
	global_load_dwordx4 v[200:203], v228, s[50:51] offset:64
	global_load_dwordx4 v[204:207], v228, s[50:51] offset:512
	global_load_dwordx4 v[208:211], v228, s[50:51] offset:576
	s_waitcnt vmcnt(4)
	v_pk_add_f32 v[80:81], v[80:81], 1.0 op_sel_hi:[1,0]
	v_pk_add_f32 v[82:83], v[82:83], 1.0 op_sel_hi:[1,0]
	v_pk_add_f32 v[84:85], v[84:85], 1.0 op_sel_hi:[1,0]
	v_pk_add_f32 v[86:87], v[86:87], 1.0 op_sel_hi:[1,0]
	v_pk_add_f32 v[88:89], v[88:89], 1.0 op_sel_hi:[1,0]
	v_pk_add_f32 v[90:91], v[90:91], 1.0 op_sel_hi:[1,0]
	v_pk_add_f32 v[92:93], v[92:93], 1.0 op_sel_hi:[1,0]
	v_pk_add_f32 v[94:95], v[94:95], 1.0 op_sel_hi:[1,0]
	v_pk_fma_f32 v[140:141], v[140:141], v[144:145], v[180:181]
	v_pk_fma_f32 v[142:143], v[142:143], v[146:147], v[182:183]
	v_pk_fma_f32 v[136:137], v[136:137], v[148:149], v[184:185]
	v_pk_fma_f32 v[138:139], v[138:139], v[150:151], v[186:187]
	v_pk_fma_f32 v[132:133], v[132:133], v[152:153], v[188:189]
	v_pk_fma_f32 v[134:135], v[134:135], v[154:155], v[190:191]
	v_pk_fma_f32 v[128:129], v[128:129], v[156:157], v[192:193]
	v_pk_fma_f32 v[130:131], v[130:131], v[158:159], v[194:195]
	s_add_u32 s62, s44, 0x0
	s_addc_u32 s63, s45, 0
	global_store_dwordx4 v228, v[140:143], s[62:63] sc1
	global_store_dwordx4 v228, v[136:139], s[62:63] offset:64 sc1
	global_store_dwordx4 v228, v[132:135], s[62:63] offset:512 sc1
	global_store_dwordx4 v228, v[128:131], s[62:63] offset:576 sc1
	v_mul_f32_e32 v232, v140, v140
	v_fmac_f32_e32 v232, v141, v141
	v_fmac_f32_e32 v232, v142, v142
	v_fmac_f32_e32 v232, v143, v143
	v_fmac_f32_e32 v232, v136, v136
	v_fmac_f32_e32 v232, v137, v137
	v_fmac_f32_e32 v232, v138, v138
	v_fmac_f32_e32 v232, v139, v139
	v_fmac_f32_e32 v232, v132, v132
	v_fmac_f32_e32 v232, v133, v133
	v_fmac_f32_e32 v232, v134, v134
	v_fmac_f32_e32 v232, v135, v135
	v_fmac_f32_e32 v232, v128, v128
	v_fmac_f32_e32 v232, v129, v129
	v_fmac_f32_e32 v232, v130, v130
	v_fmac_f32_e32 v232, v131, v131
	ds_write_b32 v230, v232 offset:0
	s_add_u32 s50, s46, 0x20000
	s_addc_u32 s51, s47, 0
	global_load_dwordx4 v[180:183], v228, s[50:51]
	global_load_dwordx4 v[184:187], v228, s[50:51] offset:64
	global_load_dwordx4 v[188:191], v228, s[50:51] offset:512
	global_load_dwordx4 v[192:195], v228, s[50:51] offset:576
	s_waitcnt vmcnt(8)
	v_pk_fma_f32 v[124:125], v[124:125], v[144:145], v[196:197]
	v_pk_fma_f32 v[126:127], v[126:127], v[146:147], v[198:199]
	v_pk_fma_f32 v[120:121], v[120:121], v[148:149], v[200:201]
	v_pk_fma_f32 v[122:123], v[122:123], v[150:151], v[202:203]
	v_pk_fma_f32 v[116:117], v[116:117], v[152:153], v[204:205]
	v_pk_fma_f32 v[118:119], v[118:119], v[154:155], v[206:207]
	v_pk_fma_f32 v[112:113], v[112:113], v[156:157], v[208:209]
	v_pk_fma_f32 v[114:115], v[114:115], v[158:159], v[210:211]
	s_add_u32 s62, s44, 0x10000
	s_addc_u32 s63, s45, 0
	global_store_dwordx4 v228, v[124:127], s[62:63] sc1
	global_store_dwordx4 v228, v[120:123], s[62:63] offset:64 sc1
	global_store_dwordx4 v228, v[116:119], s[62:63] offset:512 sc1
	global_store_dwordx4 v228, v[112:115], s[62:63] offset:576 sc1
	v_mul_f32_e32 v232, v124, v124
	v_fmac_f32_e32 v232, v125, v125
	v_fmac_f32_e32 v232, v126, v126
	v_fmac_f32_e32 v232, v127, v127
	v_fmac_f32_e32 v232, v120, v120
	v_fmac_f32_e32 v232, v121, v121
	v_fmac_f32_e32 v232, v122, v122
	v_fmac_f32_e32 v232, v123, v123
	v_fmac_f32_e32 v232, v116, v116
	v_fmac_f32_e32 v232, v117, v117
	v_fmac_f32_e32 v232, v118, v118
	v_fmac_f32_e32 v232, v119, v119
	v_fmac_f32_e32 v232, v112, v112
	v_fmac_f32_e32 v232, v113, v113
	v_fmac_f32_e32 v232, v114, v114
	v_fmac_f32_e32 v232, v115, v115
	ds_write_b32 v230, v232 offset:1024
	s_add_u32 s50, s46, 0x30000
	s_addc_u32 s51, s47, 0
	global_load_dwordx4 v[196:199], v228, s[50:51]
	global_load_dwordx4 v[200:203], v228, s[50:51] offset:64
	global_load_dwordx4 v[204:207], v228, s[50:51] offset:512
	global_load_dwordx4 v[208:211], v228, s[50:51] offset:576
	s_waitcnt vmcnt(8)
	v_pk_fma_f32 v[108:109], v[108:109], v[144:145], v[180:181]
	v_pk_fma_f32 v[110:111], v[110:111], v[146:147], v[182:183]
	v_pk_fma_f32 v[104:105], v[104:105], v[148:149], v[184:185]
	v_pk_fma_f32 v[106:107], v[106:107], v[150:151], v[186:187]
	v_pk_fma_f32 v[100:101], v[100:101], v[152:153], v[188:189]
	v_pk_fma_f32 v[102:103], v[102:103], v[154:155], v[190:191]
	v_pk_fma_f32 v[96:97], v[96:97], v[156:157], v[192:193]
	v_pk_fma_f32 v[98:99], v[98:99], v[158:159], v[194:195]
	s_add_u32 s62, s44, 0x20000
	s_addc_u32 s63, s45, 0
	global_store_dwordx4 v228, v[108:111], s[62:63] sc1
	global_store_dwordx4 v228, v[104:107], s[62:63] offset:64 sc1
	global_store_dwordx4 v228, v[100:103], s[62:63] offset:512 sc1
	global_store_dwordx4 v228, v[96:99], s[62:63] offset:576 sc1
	v_mul_f32_e32 v232, v108, v108
	v_fmac_f32_e32 v232, v109, v109
	v_fmac_f32_e32 v232, v110, v110
	v_fmac_f32_e32 v232, v111, v111
	v_fmac_f32_e32 v232, v104, v104
	v_fmac_f32_e32 v232, v105, v105
	v_fmac_f32_e32 v232, v106, v106
	v_fmac_f32_e32 v232, v107, v107
	v_fmac_f32_e32 v232, v100, v100
	v_fmac_f32_e32 v232, v101, v101
	v_fmac_f32_e32 v232, v102, v102
	v_fmac_f32_e32 v232, v103, v103
	v_fmac_f32_e32 v232, v96, v96
	v_fmac_f32_e32 v232, v97, v97
	v_fmac_f32_e32 v232, v98, v98
	v_fmac_f32_e32 v232, v99, v99
	ds_write_b32 v230, v232 offset:2048
	s_add_u32 s50, s46, 0x80000
	s_addc_u32 s51, s47, 0
	global_load_dwordx4 v[180:183], v228, s[50:51]
	global_load_dwordx4 v[184:187], v228, s[50:51] offset:64
	global_load_dwordx4 v[188:191], v228, s[50:51] offset:512
	global_load_dwordx4 v[192:195], v228, s[50:51] offset:576
	s_waitcnt vmcnt(8)
	v_pk_fma_f32 v[76:77], v[76:77], v[144:145], v[196:197]
	v_pk_fma_f32 v[78:79], v[78:79], v[146:147], v[198:199]
	v_pk_fma_f32 v[72:73], v[72:73], v[148:149], v[200:201]
	v_pk_fma_f32 v[74:75], v[74:75], v[150:151], v[202:203]
	v_pk_fma_f32 v[68:69], v[68:69], v[152:153], v[204:205]
	v_pk_fma_f32 v[70:71], v[70:71], v[154:155], v[206:207]
	v_pk_fma_f32 v[64:65], v[64:65], v[156:157], v[208:209]
	v_pk_fma_f32 v[66:67], v[66:67], v[158:159], v[210:211]
	s_add_u32 s62, s44, 0x30000
	s_addc_u32 s63, s45, 0
	global_store_dwordx4 v228, v[76:79], s[62:63] sc1
	global_store_dwordx4 v228, v[72:75], s[62:63] offset:64 sc1
	global_store_dwordx4 v228, v[68:71], s[62:63] offset:512 sc1
	global_store_dwordx4 v228, v[64:67], s[62:63] offset:576 sc1
	v_mul_f32_e32 v232, v76, v76
	v_fmac_f32_e32 v232, v77, v77
	v_fmac_f32_e32 v232, v78, v78
	v_fmac_f32_e32 v232, v79, v79
	v_fmac_f32_e32 v232, v72, v72
	v_fmac_f32_e32 v232, v73, v73
	v_fmac_f32_e32 v232, v74, v74
	v_fmac_f32_e32 v232, v75, v75
	v_fmac_f32_e32 v232, v68, v68
	v_fmac_f32_e32 v232, v69, v69
	v_fmac_f32_e32 v232, v70, v70
	v_fmac_f32_e32 v232, v71, v71
	v_fmac_f32_e32 v232, v64, v64
	v_fmac_f32_e32 v232, v65, v65
	v_fmac_f32_e32 v232, v66, v66
	v_fmac_f32_e32 v232, v67, v67
	ds_write_b32 v230, v232 offset:3072
	s_add_u32 s50, s46, 0x90000
	s_addc_u32 s51, s47, 0
	global_load_dwordx4 v[196:199], v228, s[50:51]
	global_load_dwordx4 v[200:203], v228, s[50:51] offset:64
	global_load_dwordx4 v[204:207], v228, s[50:51] offset:512
	global_load_dwordx4 v[208:211], v228, s[50:51] offset:576
	s_waitcnt vmcnt(8)
	v_pk_fma_f32 v[60:61], v[60:61], v[144:145], v[180:181]
	v_pk_fma_f32 v[62:63], v[62:63], v[146:147], v[182:183]
	v_pk_fma_f32 v[56:57], v[56:57], v[148:149], v[184:185]
	v_pk_fma_f32 v[58:59], v[58:59], v[150:151], v[186:187]
	v_pk_fma_f32 v[52:53], v[52:53], v[152:153], v[188:189]
	v_pk_fma_f32 v[54:55], v[54:55], v[154:155], v[190:191]
	v_pk_fma_f32 v[48:49], v[48:49], v[156:157], v[192:193]
	v_pk_fma_f32 v[50:51], v[50:51], v[158:159], v[194:195]
	s_add_u32 s62, s44, 0x80000
	s_addc_u32 s63, s45, 0
	global_store_dwordx4 v228, v[60:63], s[62:63] sc1
	global_store_dwordx4 v228, v[56:59], s[62:63] offset:64 sc1
	global_store_dwordx4 v228, v[52:55], s[62:63] offset:512 sc1
	global_store_dwordx4 v228, v[48:51], s[62:63] offset:576 sc1
	v_mul_f32_e32 v232, v60, v60
	v_fmac_f32_e32 v232, v61, v61
	v_fmac_f32_e32 v232, v62, v62
	v_fmac_f32_e32 v232, v63, v63
	v_fmac_f32_e32 v232, v56, v56
	v_fmac_f32_e32 v232, v57, v57
	v_fmac_f32_e32 v232, v58, v58
	v_fmac_f32_e32 v232, v59, v59
	v_fmac_f32_e32 v232, v52, v52
	v_fmac_f32_e32 v232, v53, v53
	v_fmac_f32_e32 v232, v54, v54
	v_fmac_f32_e32 v232, v55, v55
	v_fmac_f32_e32 v232, v48, v48
	v_fmac_f32_e32 v232, v49, v49
	v_fmac_f32_e32 v232, v50, v50
	v_fmac_f32_e32 v232, v51, v51
	ds_write_b32 v230, v232 offset:8192
	s_add_u32 s50, s46, 0xa0000
	s_addc_u32 s51, s47, 0
	global_load_dwordx4 v[180:183], v228, s[50:51]
	global_load_dwordx4 v[184:187], v228, s[50:51] offset:64
	global_load_dwordx4 v[188:191], v228, s[50:51] offset:512
	global_load_dwordx4 v[192:195], v228, s[50:51] offset:576
	s_waitcnt vmcnt(8)
	v_pk_fma_f32 v[44:45], v[44:45], v[144:145], v[196:197]
	v_pk_fma_f32 v[46:47], v[46:47], v[146:147], v[198:199]
	v_pk_fma_f32 v[40:41], v[40:41], v[148:149], v[200:201]
	v_pk_fma_f32 v[42:43], v[42:43], v[150:151], v[202:203]
	v_pk_fma_f32 v[36:37], v[36:37], v[152:153], v[204:205]
	v_pk_fma_f32 v[38:39], v[38:39], v[154:155], v[206:207]
	v_pk_fma_f32 v[32:33], v[32:33], v[156:157], v[208:209]
	v_pk_fma_f32 v[34:35], v[34:35], v[158:159], v[210:211]
	s_add_u32 s62, s44, 0x90000
	s_addc_u32 s63, s45, 0
	global_store_dwordx4 v228, v[44:47], s[62:63] sc1
	global_store_dwordx4 v228, v[40:43], s[62:63] offset:64 sc1
	global_store_dwordx4 v228, v[36:39], s[62:63] offset:512 sc1
	global_store_dwordx4 v228, v[32:35], s[62:63] offset:576 sc1
	v_mul_f32_e32 v232, v44, v44
	v_fmac_f32_e32 v232, v45, v45
	v_fmac_f32_e32 v232, v46, v46
	v_fmac_f32_e32 v232, v47, v47
	v_fmac_f32_e32 v232, v40, v40
	v_fmac_f32_e32 v232, v41, v41
	v_fmac_f32_e32 v232, v42, v42
	v_fmac_f32_e32 v232, v43, v43
	v_fmac_f32_e32 v232, v36, v36
	v_fmac_f32_e32 v232, v37, v37
	v_fmac_f32_e32 v232, v38, v38
	v_fmac_f32_e32 v232, v39, v39
	v_fmac_f32_e32 v232, v32, v32
	v_fmac_f32_e32 v232, v33, v33
	v_fmac_f32_e32 v232, v34, v34
	v_fmac_f32_e32 v232, v35, v35
	ds_write_b32 v230, v232 offset:9216
	s_add_u32 s50, s46, 0xb0000
	s_addc_u32 s51, s47, 0
	global_load_dwordx4 v[196:199], v228, s[50:51]
	global_load_dwordx4 v[200:203], v228, s[50:51] offset:64
	global_load_dwordx4 v[204:207], v228, s[50:51] offset:512
	global_load_dwordx4 v[208:211], v228, s[50:51] offset:576
	s_waitcnt vmcnt(8)
	v_pk_fma_f32 v[28:29], v[28:29], v[144:145], v[180:181]
	v_pk_fma_f32 v[30:31], v[30:31], v[146:147], v[182:183]
	v_pk_fma_f32 v[24:25], v[24:25], v[148:149], v[184:185]
	v_pk_fma_f32 v[26:27], v[26:27], v[150:151], v[186:187]
	v_pk_fma_f32 v[12:13], v[12:13], v[152:153], v[188:189]
	v_pk_fma_f32 v[14:15], v[14:15], v[154:155], v[190:191]
	v_pk_fma_f32 v[8:9], v[8:9], v[156:157], v[192:193]
	v_pk_fma_f32 v[10:11], v[10:11], v[158:159], v[194:195]
	s_add_u32 s62, s44, 0xa0000
	s_addc_u32 s63, s45, 0
	global_store_dwordx4 v228, v[28:31], s[62:63] sc1
	global_store_dwordx4 v228, v[24:27], s[62:63] offset:64 sc1
	global_store_dwordx4 v228, v[12:15], s[62:63] offset:512 sc1
	global_store_dwordx4 v228, v[8:11], s[62:63] offset:576 sc1
	v_mul_f32_e32 v232, v28, v28
	v_fmac_f32_e32 v232, v29, v29
	v_fmac_f32_e32 v232, v30, v30
	v_fmac_f32_e32 v232, v31, v31
	v_fmac_f32_e32 v232, v24, v24
	v_fmac_f32_e32 v232, v25, v25
	v_fmac_f32_e32 v232, v26, v26
	v_fmac_f32_e32 v232, v27, v27
	v_fmac_f32_e32 v232, v12, v12
	v_fmac_f32_e32 v232, v13, v13
	v_fmac_f32_e32 v232, v14, v14
	v_fmac_f32_e32 v232, v15, v15
	v_fmac_f32_e32 v232, v8, v8
	v_fmac_f32_e32 v232, v9, v9
	v_fmac_f32_e32 v232, v10, v10
	v_fmac_f32_e32 v232, v11, v11
	ds_write_b32 v230, v232 offset:10240
	s_waitcnt vmcnt(4)
	v_pk_fma_f32 v[20:21], v[20:21], v[144:145], v[196:197]
	v_pk_fma_f32 v[22:23], v[22:23], v[146:147], v[198:199]
	v_pk_fma_f32 v[16:17], v[16:17], v[148:149], v[200:201]
	v_pk_fma_f32 v[18:19], v[18:19], v[150:151], v[202:203]
	v_pk_fma_f32 v[4:5], v[4:5], v[152:153], v[204:205]
	v_pk_fma_f32 v[6:7], v[6:7], v[154:155], v[206:207]
	v_pk_fma_f32 v[0:1], v[0:1], v[156:157], v[208:209]
	v_pk_fma_f32 v[2:3], v[2:3], v[158:159], v[210:211]
	s_add_u32 s62, s44, 0xb0000
	s_addc_u32 s63, s45, 0
	global_store_dwordx4 v228, v[20:23], s[62:63] sc1
	global_store_dwordx4 v228, v[16:19], s[62:63] offset:64 sc1
	global_store_dwordx4 v228, v[4:7], s[62:63] offset:512 sc1
	global_store_dwordx4 v228, v[0:3], s[62:63] offset:576 sc1
	v_mul_f32_e32 v232, v20, v20
	v_fmac_f32_e32 v232, v21, v21
	v_fmac_f32_e32 v232, v22, v22
	v_fmac_f32_e32 v232, v23, v23
	v_fmac_f32_e32 v232, v16, v16
	v_fmac_f32_e32 v232, v17, v17
	v_fmac_f32_e32 v232, v18, v18
	v_fmac_f32_e32 v232, v19, v19
	v_fmac_f32_e32 v232, v4, v4
	v_fmac_f32_e32 v232, v5, v5
	v_fmac_f32_e32 v232, v6, v6
	v_fmac_f32_e32 v232, v7, v7
	v_fmac_f32_e32 v232, v0, v0
	v_fmac_f32_e32 v232, v1, v1
	v_fmac_f32_e32 v232, v2, v2
	v_fmac_f32_e32 v232, v3, v3
	ds_write_b32 v230, v232 offset:11264
	global_load_dwordx4 v[144:147], v229, s[60:61]
	global_load_dwordx4 v[148:151], v229, s[60:61] offset:64
	global_load_dwordx4 v[152:155], v229, s[60:61] offset:512
	global_load_dwordx4 v[156:159], v229, s[60:61] offset:576
	s_waitcnt lgkmcnt(0)
	s_barrier
	v_cmp_gt_u32_e32 vcc, 0x100, v177
	s_and_saveexec_b64 s[0:1], vcc
	s_cbranch_execz .Lf2_nored
	v_lshlrev_b32_e32 v233, 6, v177
	ds_read_b128 v[236:239], v233
	ds_read_b128 v[240:243], v233 offset:16
	ds_read_b128 v[244:247], v233 offset:32
	ds_read_b128 v[248:251], v233 offset:48
	s_lshl_b32 s11, s9, 8
	v_add_u32_e32 v234, s11, v177
	v_lshlrev_b32_e32 v234, 4, v234
	s_lshl_b32 s11, s10, 2
	v_add_u32_e32 v234, s11, v234
	s_waitcnt lgkmcnt(0)
	v_add_f32_e32 v236, v236, v237
	v_add_f32_e32 v236, v236, v238
	v_add_f32_e32 v236, v236, v239
	v_add_f32_e32 v236, v236, v240
	v_add_f32_e32 v236, v236, v241
	v_add_f32_e32 v236, v236, v242
	v_add_f32_e32 v236, v236, v243
	v_add_f32_e32 v236, v236, v244
	v_add_f32_e32 v236, v236, v245
	v_add_f32_e32 v236, v236, v246
	v_add_f32_e32 v236, v236, v247
	v_add_f32_e32 v236, v236, v248
	v_add_f32_e32 v236, v236, v249
	v_add_f32_e32 v236, v236, v250
	v_add_f32_e32 v236, v236, v251
	global_store_dword v234, v236, s[52:53]

.Lf2_bar_end_b:
	s_or_b64 exec, exec, s[0:1]
	s_barrier
	v_lshrrev_b32_e32 v232, 12, v228
	v_lshlrev_b32_e32 v232, 4, v232
	v_add_u32_e32 v233, 0x0, v232
	v_add_u32_e32 v234, 0x100, v232
	v_add_u32_e32 v235, 0x200, v232
	v_add_u32_e32 v236, 0x300, v232
	v_add_u32_e32 v237, 0x800, v232
	v_add_u32_e32 v238, 0x900, v232
	v_add_u32_e32 v239, 0xa00, v232
	v_add_u32_e32 v240, 0xb00, v232
	global_load_dwordx4 v[180:183], v233, s[52:53]
	global_load_dwordx4 v[184:187], v234, s[52:53]
	global_load_dwordx4 v[188:191], v235, s[52:53]
	global_load_dwordx4 v[192:195], v236, s[52:53]
	global_load_dwordx4 v[196:199], v237, s[52:53]
	global_load_dwordx4 v[200:203], v238, s[52:53]
	global_load_dwordx4 v[204:207], v239, s[52:53]
	global_load_dwordx4 v[208:211], v240, s[52:53]
	s_waitcnt vmcnt(0)
	v_mov_b32_e32 v242, 0x3a800000
	v_mov_b32_e32 v243, 0x358637bd
	v_add_f32_e32 v212, v180, v181
	v_add_f32_e32 v212, v212, v182
	v_add_f32_e32 v212, v212, v183
	v_fma_f32 v212, v212, v242, v243
	v_add_f32_e32 v214, v184, v185
	v_add_f32_e32 v214, v214, v186
	v_add_f32_e32 v214, v214, v187
	v_fma_f32 v214, v214, v242, v243
	v_add_f32_e32 v216, v188, v189
	v_add_f32_e32 v216, v216, v190
	v_add_f32_e32 v216, v216, v191
	v_fma_f32 v216, v216, v242, v243
	v_add_f32_e32 v218, v192, v193
	v_add_f32_e32 v218, v218, v194
	v_add_f32_e32 v218, v218, v195
	v_fma_f32 v218, v218, v242, v243
	v_add_f32_e32 v220, v196, v197
	v_add_f32_e32 v220, v220, v198
	v_add_f32_e32 v220, v220, v199
	v_fma_f32 v220, v220, v242, v243
	v_add_f32_e32 v222, v200, v201
	v_add_f32_e32 v222, v222, v202
	v_add_f32_e32 v222, v222, v203
	v_fma_f32 v222, v222, v242, v243
	v_add_f32_e32 v224, v204, v205
	v_add_f32_e32 v224, v224, v206
	v_add_f32_e32 v224, v224, v207
	v_fma_f32 v224, v224, v242, v243
	v_add_f32_e32 v226, v208, v209
	v_add_f32_e32 v226, v226, v210
	v_add_f32_e32 v226, v226, v211
	v_fma_f32 v226, v226, v242, v243
	v_rsq_f32_e32 v212, v212
	v_rsq_f32_e32 v214, v214
	v_rsq_f32_e32 v216, v216
	v_rsq_f32_e32 v218, v218
	v_rsq_f32_e32 v220, v220
	v_rsq_f32_e32 v222, v222
	v_rsq_f32_e32 v224, v224
	v_rsq_f32_e32 v226, v226
	s_nop 0
	s_add_u32 s62, s54, 0x0
	s_addc_u32 s63, s55, 0
	v_pk_mul_f32 v[140:141], v[140:141], v[212:213] op_sel_hi:[1,0]
	v_pk_mul_f32 v[142:143], v[142:143], v[212:213] op_sel_hi:[1,0]
	v_pk_mul_f32 v[140:141], v[160:161], v[140:141]
	v_pk_mul_f32 v[142:143], v[162:163], v[142:143]
	v_pk_fma_f32 v[140:141], v[80:81], v[140:141], v[144:145]
	v_pk_fma_f32 v[142:143], v[82:83], v[142:143], v[146:147]
	v_pk_mul_f32 v[136:137], v[136:137], v[212:213] op_sel_hi:[1,0]
	v_pk_mul_f32 v[138:139], v[138:139], v[212:213] op_sel_hi:[1,0]
	v_pk_mul_f32 v[136:137], v[164:165], v[136:137]
	v_pk_mul_f32 v[138:139], v[166:167], v[138:139]
	v_pk_fma_f32 v[136:137], v[84:85], v[136:137], v[148:149]
	v_pk_fma_f32 v[138:139], v[86:87], v[138:139], v[150:151]
	v_pk_mul_f32 v[132:133], v[132:133], v[212:213] op_sel_hi:[1,0]
	v_pk_mul_f32 v[134:135], v[134:135], v[212:213] op_sel_hi:[1,0]
	v_pk_mul_f32 v[132:133], v[168:169], v[132:133]
	v_pk_mul_f32 v[134:135], v[170:171], v[134:135]
	v_pk_fma_f32 v[132:133], v[88:89], v[132:133], v[152:153]
	v_pk_fma_f32 v[134:135], v[90:91], v[134:135], v[154:155]
	v_pk_mul_f32 v[128:129], v[128:129], v[212:213] op_sel_hi:[1,0]
	v_pk_mul_f32 v[130:131], v[130:131], v[212:213] op_sel_hi:[1,0]
	v_pk_mul_f32 v[128:129], v[172:173], v[128:129]
	v_pk_mul_f32 v[130:131], v[174:175], v[130:131]
	v_pk_fma_f32 v[128:129], v[92:93], v[128:129], v[156:157]
	v_pk_fma_f32 v[130:131], v[94:95], v[130:131], v[158:159]
	v_cvt_pk_bf16_f32 v236, v140, v141
	v_cvt_pk_bf16_f32 v237, v142, v143
	v_cvt_pk_bf16_f32 v238, v136, v137
	v_cvt_pk_bf16_f32 v239, v138, v139
	s_nop 1
	v_permlane16_swap_b32 v236, v238
	v_permlane16_swap_b32 v237, v239
	global_store_dwordx4 v231, v[236:239], s[62:63] sc1
	v_cvt_pk_bf16_f32 v240, v132, v133
	v_cvt_pk_bf16_f32 v241, v134, v135
	v_cvt_pk_bf16_f32 v242, v128, v129
	v_cvt_pk_bf16_f32 v243, v130, v131
	s_nop 1
	v_permlane16_swap_b32 v240, v242
	v_permlane16_swap_b32 v241, v243
	global_store_dwordx4 v231, v[240:243], s[62:63] offset:256 sc1
	s_add_u32 s62, s54, 0x8000
	s_addc_u32 s63, s55, 0
	v_pk_mul_f32 v[124:125], v[124:125], v[214:215] op_sel_hi:[1,0]
	v_pk_mul_f32 v[126:127], v[126:127], v[214:215] op_sel_hi:[1,0]
	v_pk_mul_f32 v[124:125], v[160:161], v[124:125]
	v_pk_mul_f32 v[126:127], v[162:163], v[126:127]
	v_pk_fma_f32 v[124:125], v[80:81], v[124:125], v[144:145]
	v_pk_fma_f32 v[126:127], v[82:83], v[126:127], v[146:147]
	v_pk_mul_f32 v[120:121], v[120:121], v[214:215] op_sel_hi:[1,0]
	v_pk_mul_f32 v[122:123], v[122:123], v[214:215] op_sel_hi:[1,0]
	v_pk_mul_f32 v[120:121], v[164:165], v[120:121]
	v_pk_mul_f32 v[122:123], v[166:167], v[122:123]
	v_pk_fma_f32 v[120:121], v[84:85], v[120:121], v[148:149]
	v_pk_fma_f32 v[122:123], v[86:87], v[122:123], v[150:151]
	v_pk_mul_f32 v[116:117], v[116:117], v[214:215] op_sel_hi:[1,0]
	v_pk_mul_f32 v[118:119], v[118:119], v[214:215] op_sel_hi:[1,0]
	v_pk_mul_f32 v[116:117], v[168:169], v[116:117]
	v_pk_mul_f32 v[118:119], v[170:171], v[118:119]
	v_pk_fma_f32 v[116:117], v[88:89], v[116:117], v[152:153]
	v_pk_fma_f32 v[118:119], v[90:91], v[118:119], v[154:155]
	v_pk_mul_f32 v[112:113], v[112:113], v[214:215] op_sel_hi:[1,0]
	v_pk_mul_f32 v[114:115], v[114:115], v[214:215] op_sel_hi:[1,0]
	v_pk_mul_f32 v[112:113], v[172:173], v[112:113]
	v_pk_mul_f32 v[114:115], v[174:175], v[114:115]
	v_pk_fma_f32 v[112:113], v[92:93], v[112:113], v[156:157]
	v_pk_fma_f32 v[114:115], v[94:95], v[114:115], v[158:159]
	v_cvt_pk_bf16_f32 v244, v124, v125
	v_cvt_pk_bf16_f32 v245, v126, v127
	v_cvt_pk_bf16_f32 v246, v120, v121
	v_cvt_pk_bf16_f32 v247, v122, v123
	s_nop 1
	v_permlane16_swap_b32 v244, v246
	v_permlane16_swap_b32 v245, v247
	global_store_dwordx4 v231, v[244:247], s[62:63] sc1
	v_cvt_pk_bf16_f32 v248, v116, v117
	v_cvt_pk_bf16_f32 v249, v118, v119
	v_cvt_pk_bf16_f32 v250, v112, v113
	v_cvt_pk_bf16_f32 v251, v114, v115
	s_nop 1
	v_permlane16_swap_b32 v248, v250
	v_permlane16_swap_b32 v249, v251
	global_store_dwordx4 v231, v[248:251], s[62:63] offset:256 sc1
	s_add_u32 s62, s54, 0x10000
	s_addc_u32 s63, s55, 0
	v_pk_mul_f32 v[108:109], v[108:109], v[216:217] op_sel_hi:[1,0]
	v_pk_mul_f32 v[110:111], v[110:111], v[216:217] op_sel_hi:[1,0]
	v_pk_mul_f32 v[108:109], v[160:161], v[108:109]
	v_pk_mul_f32 v[110:111], v[162:163], v[110:111]
	v_pk_fma_f32 v[108:109], v[80:81], v[108:109], v[144:145]
	v_pk_fma_f32 v[110:111], v[82:83], v[110:111], v[146:147]
	v_pk_mul_f32 v[104:105], v[104:105], v[216:217] op_sel_hi:[1,0]
	v_pk_mul_f32 v[106:107], v[106:107], v[216:217] op_sel_hi:[1,0]
	v_pk_mul_f32 v[104:105], v[164:165], v[104:105]
	v_pk_mul_f32 v[106:107], v[166:167], v[106:107]
	v_pk_fma_f32 v[104:105], v[84:85], v[104:105], v[148:149]
	v_pk_fma_f32 v[106:107], v[86:87], v[106:107], v[150:151]
	v_pk_mul_f32 v[100:101], v[100:101], v[216:217] op_sel_hi:[1,0]
	v_pk_mul_f32 v[102:103], v[102:103], v[216:217] op_sel_hi:[1,0]
	v_pk_mul_f32 v[100:101], v[168:169], v[100:101]
	v_pk_mul_f32 v[102:103], v[170:171], v[102:103]
	v_pk_fma_f32 v[100:101], v[88:89], v[100:101], v[152:153]
	v_pk_fma_f32 v[102:103], v[90:91], v[102:103], v[154:155]
	v_pk_mul_f32 v[96:97], v[96:97], v[216:217] op_sel_hi:[1,0]
	v_pk_mul_f32 v[98:99], v[98:99], v[216:217] op_sel_hi:[1,0]
	v_pk_mul_f32 v[96:97], v[172:173], v[96:97]
	v_pk_mul_f32 v[98:99], v[174:175], v[98:99]
	v_pk_fma_f32 v[96:97], v[92:93], v[96:97], v[156:157]
	v_pk_fma_f32 v[98:99], v[94:95], v[98:99], v[158:159]
	v_cvt_pk_bf16_f32 v236, v108, v109
	v_cvt_pk_bf16_f32 v237, v110, v111
	v_cvt_pk_bf16_f32 v238, v104, v105
	v_cvt_pk_bf16_f32 v239, v106, v107
	s_nop 1
	v_permlane16_swap_b32 v236, v238
	v_permlane16_swap_b32 v237, v239
	global_store_dwordx4 v231, v[236:239], s[62:63] sc1
	v_cvt_pk_bf16_f32 v240, v100, v101
	v_cvt_pk_bf16_f32 v241, v102, v103
	v_cvt_pk_bf16_f32 v242, v96, v97
	v_cvt_pk_bf16_f32 v243, v98, v99
	s_nop 1
	v_permlane16_swap_b32 v240, v242
	v_permlane16_swap_b32 v241, v243
	global_store_dwordx4 v231, v[240:243], s[62:63] offset:256 sc1
	s_add_u32 s62, s54, 0x18000
	s_addc_u32 s63, s55, 0
	v_pk_mul_f32 v[76:77], v[76:77], v[218:219] op_sel_hi:[1,0]
	v_pk_mul_f32 v[78:79], v[78:79], v[218:219] op_sel_hi:[1,0]
	v_pk_mul_f32 v[76:77], v[160:161], v[76:77]
	v_pk_mul_f32 v[78:79], v[162:163], v[78:79]
	v_pk_fma_f32 v[76:77], v[80:81], v[76:77], v[144:145]
	v_pk_fma_f32 v[78:79], v[82:83], v[78:79], v[146:147]
	v_pk_mul_f32 v[72:73], v[72:73], v[218:219] op_sel_hi:[1,0]
	v_pk_mul_f32 v[74:75], v[74:75], v[218:219] op_sel_hi:[1,0]
	v_pk_mul_f32 v[72:73], v[164:165], v[72:73]
	v_pk_mul_f32 v[74:75], v[166:167], v[74:75]
	v_pk_fma_f32 v[72:73], v[84:85], v[72:73], v[148:149]
	v_pk_fma_f32 v[74:75], v[86:87], v[74:75], v[150:151]
	v_pk_mul_f32 v[68:69], v[68:69], v[218:219] op_sel_hi:[1,0]
	v_pk_mul_f32 v[70:71], v[70:71], v[218:219] op_sel_hi:[1,0]
	v_pk_mul_f32 v[68:69], v[168:169], v[68:69]
	v_pk_mul_f32 v[70:71], v[170:171], v[70:71]
	v_pk_fma_f32 v[68:69], v[88:89], v[68:69], v[152:153]
	v_pk_fma_f32 v[70:71], v[90:91], v[70:71], v[154:155]
	v_pk_mul_f32 v[64:65], v[64:65], v[218:219] op_sel_hi:[1,0]
	v_pk_mul_f32 v[66:67], v[66:67], v[218:219] op_sel_hi:[1,0]
	v_pk_mul_f32 v[64:65], v[172:173], v[64:65]
	v_pk_mul_f32 v[66:67], v[174:175], v[66:67]
	v_pk_fma_f32 v[64:65], v[92:93], v[64:65], v[156:157]
	v_pk_fma_f32 v[66:67], v[94:95], v[66:67], v[158:159]
	v_cvt_pk_bf16_f32 v244, v76, v77
	v_cvt_pk_bf16_f32 v245, v78, v79
	v_cvt_pk_bf16_f32 v246, v72, v73
	v_cvt_pk_bf16_f32 v247, v74, v75
	s_nop 1
	v_permlane16_swap_b32 v244, v246
	v_permlane16_swap_b32 v245, v247
	global_store_dwordx4 v231, v[244:247], s[62:63] sc1
	v_cvt_pk_bf16_f32 v248, v68, v69
	v_cvt_pk_bf16_f32 v249, v70, v71
	v_cvt_pk_bf16_f32 v250, v64, v65
	v_cvt_pk_bf16_f32 v251, v66, v67
	s_nop 1
	v_permlane16_swap_b32 v248, v250
	v_permlane16_swap_b32 v249, v251
	global_store_dwordx4 v231, v[248:251], s[62:63] offset:256 sc1
	s_add_u32 s62, s54, 0x40000
	s_addc_u32 s63, s55, 0
	v_pk_mul_f32 v[60:61], v[60:61], v[220:221] op_sel_hi:[1,0]
	v_pk_mul_f32 v[62:63], v[62:63], v[220:221] op_sel_hi:[1,0]
	v_pk_mul_f32 v[60:61], v[160:161], v[60:61]
	v_pk_mul_f32 v[62:63], v[162:163], v[62:63]
	v_pk_fma_f32 v[60:61], v[80:81], v[60:61], v[144:145]
	v_pk_fma_f32 v[62:63], v[82:83], v[62:63], v[146:147]
	v_pk_mul_f32 v[56:57], v[56:57], v[220:221] op_sel_hi:[1,0]
	v_pk_mul_f32 v[58:59], v[58:59], v[220:221] op_sel_hi:[1,0]
	v_pk_mul_f32 v[56:57], v[164:165], v[56:57]
	v_pk_mul_f32 v[58:59], v[166:167], v[58:59]
	v_pk_fma_f32 v[56:57], v[84:85], v[56:57], v[148:149]
	v_pk_fma_f32 v[58:59], v[86:87], v[58:59], v[150:151]
	v_pk_mul_f32 v[52:53], v[52:53], v[220:221] op_sel_hi:[1,0]
	v_pk_mul_f32 v[54:55], v[54:55], v[220:221] op_sel_hi:[1,0]
	v_pk_mul_f32 v[52:53], v[168:169], v[52:53]
	v_pk_mul_f32 v[54:55], v[170:171], v[54:55]
	v_pk_fma_f32 v[52:53], v[88:89], v[52:53], v[152:153]
	v_pk_fma_f32 v[54:55], v[90:91], v[54:55], v[154:155]
	v_pk_mul_f32 v[48:49], v[48:49], v[220:221] op_sel_hi:[1,0]
	v_pk_mul_f32 v[50:51], v[50:51], v[220:221] op_sel_hi:[1,0]
	v_pk_mul_f32 v[48:49], v[172:173], v[48:49]
	v_pk_mul_f32 v[50:51], v[174:175], v[50:51]
	v_pk_fma_f32 v[48:49], v[92:93], v[48:49], v[156:157]
	v_pk_fma_f32 v[50:51], v[94:95], v[50:51], v[158:159]
	v_cvt_pk_bf16_f32 v236, v60, v61
	v_cvt_pk_bf16_f32 v237, v62, v63
	v_cvt_pk_bf16_f32 v238, v56, v57
	v_cvt_pk_bf16_f32 v239, v58, v59
	s_nop 1
	v_permlane16_swap_b32 v236, v238
	v_permlane16_swap_b32 v237, v239
	global_store_dwordx4 v231, v[236:239], s[62:63] sc1
	v_cvt_pk_bf16_f32 v240, v52, v53
	v_cvt_pk_bf16_f32 v241, v54, v55
	v_cvt_pk_bf16_f32 v242, v48, v49
	v_cvt_pk_bf16_f32 v243, v50, v51
	s_nop 1
	v_permlane16_swap_b32 v240, v242
	v_permlane16_swap_b32 v241, v243
	global_store_dwordx4 v231, v[240:243], s[62:63] offset:256 sc1
	s_add_u32 s62, s54, 0x48000
	s_addc_u32 s63, s55, 0
	v_pk_mul_f32 v[44:45], v[44:45], v[222:223] op_sel_hi:[1,0]
	v_pk_mul_f32 v[46:47], v[46:47], v[222:223] op_sel_hi:[1,0]
	v_pk_mul_f32 v[44:45], v[160:161], v[44:45]
	v_pk_mul_f32 v[46:47], v[162:163], v[46:47]
	v_pk_fma_f32 v[44:45], v[80:81], v[44:45], v[144:145]
	v_pk_fma_f32 v[46:47], v[82:83], v[46:47], v[146:147]
	v_pk_mul_f32 v[40:41], v[40:41], v[222:223] op_sel_hi:[1,0]
	v_pk_mul_f32 v[42:43], v[42:43], v[222:223] op_sel_hi:[1,0]
	v_pk_mul_f32 v[40:41], v[164:165], v[40:41]
	v_pk_mul_f32 v[42:43], v[166:167], v[42:43]
	v_pk_fma_f32 v[40:41], v[84:85], v[40:41], v[148:149]
	v_pk_fma_f32 v[42:43], v[86:87], v[42:43], v[150:151]
	v_pk_mul_f32 v[36:37], v[36:37], v[222:223] op_sel_hi:[1,0]
	v_pk_mul_f32 v[38:39], v[38:39], v[222:223] op_sel_hi:[1,0]
	v_pk_mul_f32 v[36:37], v[168:169], v[36:37]
	v_pk_mul_f32 v[38:39], v[170:171], v[38:39]
	v_pk_fma_f32 v[36:37], v[88:89], v[36:37], v[152:153]
	v_pk_fma_f32 v[38:39], v[90:91], v[38:39], v[154:155]
	v_pk_mul_f32 v[32:33], v[32:33], v[222:223] op_sel_hi:[1,0]
	v_pk_mul_f32 v[34:35], v[34:35], v[222:223] op_sel_hi:[1,0]
	v_pk_mul_f32 v[32:33], v[172:173], v[32:33]
	v_pk_mul_f32 v[34:35], v[174:175], v[34:35]
	v_pk_fma_f32 v[32:33], v[92:93], v[32:33], v[156:157]
	v_pk_fma_f32 v[34:35], v[94:95], v[34:35], v[158:159]
	v_cvt_pk_bf16_f32 v244, v44, v45
	v_cvt_pk_bf16_f32 v245, v46, v47
	v_cvt_pk_bf16_f32 v246, v40, v41
	v_cvt_pk_bf16_f32 v247, v42, v43
	s_nop 1
	v_permlane16_swap_b32 v244, v246
	v_permlane16_swap_b32 v245, v247
	global_store_dwordx4 v231, v[244:247], s[62:63] sc1
	v_cvt_pk_bf16_f32 v248, v36, v37
	v_cvt_pk_bf16_f32 v249, v38, v39
	v_cvt_pk_bf16_f32 v250, v32, v33
	v_cvt_pk_bf16_f32 v251, v34, v35
	s_nop 1
	v_permlane16_swap_b32 v248, v250
	v_permlane16_swap_b32 v249, v251
	global_store_dwordx4 v231, v[248:251], s[62:63] offset:256 sc1
	s_add_u32 s62, s54, 0x50000
	s_addc_u32 s63, s55, 0
	v_pk_mul_f32 v[28:29], v[28:29], v[224:225] op_sel_hi:[1,0]
	v_pk_mul_f32 v[30:31], v[30:31], v[224:225] op_sel_hi:[1,0]
	v_pk_mul_f32 v[28:29], v[160:161], v[28:29]
	v_pk_mul_f32 v[30:31], v[162:163], v[30:31]
	v_pk_fma_f32 v[28:29], v[80:81], v[28:29], v[144:145]
	v_pk_fma_f32 v[30:31], v[82:83], v[30:31], v[146:147]
	v_pk_mul_f32 v[24:25], v[24:25], v[224:225] op_sel_hi:[1,0]
	v_pk_mul_f32 v[26:27], v[26:27], v[224:225] op_sel_hi:[1,0]
	v_pk_mul_f32 v[24:25], v[164:165], v[24:25]
	v_pk_mul_f32 v[26:27], v[166:167], v[26:27]
	v_pk_fma_f32 v[24:25], v[84:85], v[24:25], v[148:149]
	v_pk_fma_f32 v[26:27], v[86:87], v[26:27], v[150:151]
	v_pk_mul_f32 v[12:13], v[12:13], v[224:225] op_sel_hi:[1,0]
	v_pk_mul_f32 v[14:15], v[14:15], v[224:225] op_sel_hi:[1,0]
	v_pk_mul_f32 v[12:13], v[168:169], v[12:13]
	v_pk_mul_f32 v[14:15], v[170:171], v[14:15]
	v_pk_fma_f32 v[12:13], v[88:89], v[12:13], v[152:153]
	v_pk_fma_f32 v[14:15], v[90:91], v[14:15], v[154:155]
	v_pk_mul_f32 v[8:9], v[8:9], v[224:225] op_sel_hi:[1,0]
	v_pk_mul_f32 v[10:11], v[10:11], v[224:225] op_sel_hi:[1,0]
	v_pk_mul_f32 v[8:9], v[172:173], v[8:9]
	v_pk_mul_f32 v[10:11], v[174:175], v[10:11]
	v_pk_fma_f32 v[8:9], v[92:93], v[8:9], v[156:157]
	v_pk_fma_f32 v[10:11], v[94:95], v[10:11], v[158:159]
	v_cvt_pk_bf16_f32 v236, v28, v29
	v_cvt_pk_bf16_f32 v237, v30, v31
	v_cvt_pk_bf16_f32 v238, v24, v25
	v_cvt_pk_bf16_f32 v239, v26, v27
	s_nop 1
	v_permlane16_swap_b32 v236, v238
	v_permlane16_swap_b32 v237, v239
	global_store_dwordx4 v231, v[236:239], s[62:63] sc1
	v_cvt_pk_bf16_f32 v240, v12, v13
	v_cvt_pk_bf16_f32 v241, v14, v15
	v_cvt_pk_bf16_f32 v242, v8, v9
	v_cvt_pk_bf16_f32 v243, v10, v11
	s_nop 1
	v_permlane16_swap_b32 v240, v242
	v_permlane16_swap_b32 v241, v243
	global_store_dwordx4 v231, v[240:243], s[62:63] offset:256 sc1
	s_add_u32 s62, s54, 0x58000
	s_addc_u32 s63, s55, 0
	v_pk_mul_f32 v[20:21], v[20:21], v[226:227] op_sel_hi:[1,0]
	v_pk_mul_f32 v[22:23], v[22:23], v[226:227] op_sel_hi:[1,0]
	v_pk_mul_f32 v[20:21], v[160:161], v[20:21]
	v_pk_mul_f32 v[22:23], v[162:163], v[22:23]
	v_pk_fma_f32 v[20:21], v[80:81], v[20:21], v[144:145]
	v_pk_fma_f32 v[22:23], v[82:83], v[22:23], v[146:147]
	v_pk_mul_f32 v[16:17], v[16:17], v[226:227] op_sel_hi:[1,0]
	v_pk_mul_f32 v[18:19], v[18:19], v[226:227] op_sel_hi:[1,0]
	v_pk_mul_f32 v[16:17], v[164:165], v[16:17]
	v_pk_mul_f32 v[18:19], v[166:167], v[18:19]
	v_pk_fma_f32 v[16:17], v[84:85], v[16:17], v[148:149]
	v_pk_fma_f32 v[18:19], v[86:87], v[18:19], v[150:151]
	v_pk_mul_f32 v[4:5], v[4:5], v[226:227] op_sel_hi:[1,0]
	v_pk_mul_f32 v[6:7], v[6:7], v[226:227] op_sel_hi:[1,0]
	v_pk_mul_f32 v[4:5], v[168:169], v[4:5]
	v_pk_mul_f32 v[6:7], v[170:171], v[6:7]
	v_pk_fma_f32 v[4:5], v[88:89], v[4:5], v[152:153]
	v_pk_fma_f32 v[6:7], v[90:91], v[6:7], v[154:155]
	v_pk_mul_f32 v[0:1], v[0:1], v[226:227] op_sel_hi:[1,0]
	v_pk_mul_f32 v[2:3], v[2:3], v[226:227] op_sel_hi:[1,0]
	v_pk_mul_f32 v[0:1], v[172:173], v[0:1]
	v_pk_mul_f32 v[2:3], v[174:175], v[2:3]
	v_pk_fma_f32 v[0:1], v[92:93], v[0:1], v[156:157]
	v_pk_fma_f32 v[2:3], v[94:95], v[2:3], v[158:159]
	v_cvt_pk_bf16_f32 v244, v20, v21
	v_cvt_pk_bf16_f32 v245, v22, v23
	v_cvt_pk_bf16_f32 v246, v16, v17
	v_cvt_pk_bf16_f32 v247, v18, v19
	s_nop 1
	v_permlane16_swap_b32 v244, v246
	v_permlane16_swap_b32 v245, v247
	global_store_dwordx4 v231, v[244:247], s[62:63] sc1
	v_cvt_pk_bf16_f32 v248, v4, v5
	v_cvt_pk_bf16_f32 v249, v6, v7
	v_cvt_pk_bf16_f32 v250, v0, v1
	v_cvt_pk_bf16_f32 v251, v2, v3
	s_nop 1
	v_permlane16_swap_b32 v248, v250
	v_permlane16_swap_b32 v249, v251
	global_store_dwordx4 v231, v[248:251], s[62:63] offset:256 sc1
	v_readlane_b32 s16, v253, 9
	v_readlane_b32 s17, v253, 10
	v_readlane_b32 s34, v254, 63
	v_readlane_b32 s35, v255, 0
	s_waitcnt vmcnt(0)
	s_barrier
	s_and_saveexec_b64 s[0:1], s[34:35]
	s_cbranch_execz .LBB0_1371
	s_add_u32 s98, s98, 1
	v_mov_b32_e32 v7, 0x26c00
	ds_read2_b32 v[8:9], v7 offset1:1
	v_mov_b32_e32 v2, s99
	v_mov_b32_e32 v3, 1
	global_atomic_add v4, v2, v3, s[100:101] sc0
	v_add_u32_e32 v2, 0x1000, v2
	v_mov_b32_e32 v10, 0x2480
	s_waitcnt vmcnt(0) lgkmcnt(0)
	v_add_u32_e32 v4, 1, v4
	v_mul_lo_u32 v5, v8, s98
	v_mul_lo_u32 v9, v9, s98
	v_cmp_eq_u32_e32 vcc, v4, v5
	s_and_saveexec_b64 s[4:5], vcc
	s_cbranch_execz .Lh2_skip_7
	buffer_wbl2 sc1
	s_waitcnt vmcnt(0)
	global_atomic_add v10, v3, s[100:101]
	global_atomic_add v10, v3, s[100:101] offset:256
	global_atomic_add v10, v3, s[100:101] offset:512
	global_atomic_add v10, v3, s[100:101] offset:768
	global_atomic_add v10, v3, s[100:101] offset:1024
	global_atomic_add v10, v3, s[100:101] offset:1280
	global_atomic_add v10, v3, s[100:101] offset:1536
	global_atomic_add v10, v3, s[100:101] offset:1792
	global_atomic_add v10, v3, s[100:101] offset:2048
	global_atomic_add v10, v3, s[100:101] offset:2304
	global_atomic_add v10, v3, s[100:101] offset:2560
	global_atomic_add v10, v3, s[100:101] offset:2816
	global_atomic_add v10, v3, s[100:101] offset:3072
	global_atomic_add v10, v3, s[100:101] offset:3328
	global_atomic_add v10, v3, s[100:101] offset:3584
	global_atomic_add v10, v3, s[100:101] offset:3840
